# int8 SwiGLU epilogue fp8 path: 32-bit saddr store addressing (v_mad_u32_u24 + global_store saddr) instead of 64-bit mad/add chains, dropped redundant zero-init before cvt_pk_fp8
# speedup vs baseline: 1.0030x; 1.0030x over previous
.LBB0_297:
	v_mov_b32_e32 v132, v240
	v_cvt_f32_i32_e32 v125, v125
	v_readfirstlane_b32 s17, v132
	s_ashr_i32 s21, s17, 2
	s_lshr_b32 s17, s17, 1
	s_and_b32 s17, s17, 0x60
	v_and_b32_e32 v166, 15, v132
	v_lshrrev_b32_e32 v132, 1, v132
	s_lshl_b32 s27, s17, 2
	v_and_b32_e32 v167, 24, v132
	s_add_i32 s27, s27, 0
	v_lshl_add_u32 v132, v167, 2, s27
	v_add_u32_e32 v140, 0x21600, v132
	ds_read_b128 v[132:135], v140 offset:512
	ds_read_b128 v[136:139], v140 offset:528
	s_andn2_b32 s21, s21, 63
	ds_read_b128 v[158:161], v140
	ds_read_b128 v[162:165], v140 offset:16
	s_lshl_b32 s27, s21, 2
	s_add_i32 s27, s27, 0
	v_lshl_add_u32 v140, v166, 2, s27
	s_waitcnt lgkmcnt(0)
	v_pk_mul_f32 v[132:133], v[216:217], v[132:133]
	v_add_u32_e32 v140, 0x21200, v140
	v_pk_mul_f32 v[150:151], v[158:159], s[48:49] op_sel_hi:[1,0]
	v_pk_mul_f32 v[146:147], v[158:159], v[132:133]
	v_cvt_f32_i32_e32 v159, v129
	v_cvt_f32_i32_e32 v158, v128
	v_cvt_f32_i32_e32 v124, v124
	v_mov_b32_e32 v197, v196
	ds_read2_b32 v[156:157], v140 offset1:16
	ds_read2_b32 v[154:155], v140 offset0:32 offset1:48
	ds_read2_b32 v[152:153], v140 offset0:128 offset1:144
	ds_read2_b32 v[148:149], v140 offset0:160 offset1:176
	v_pk_mul_f32 v[138:139], v[196:197], v[138:139]
	v_pk_mul_f32 v[136:137], v[216:217], v[136:137]
	v_pk_mul_f32 v[134:135], v[196:197], v[134:135]
	v_cvt_f32_i32_e32 v131, v131
	v_cvt_f32_i32_e32 v130, v130
	v_cvt_f32_i32_e32 v127, v127
	v_cvt_f32_i32_e32 v126, v126
	v_pk_mul_f32 v[142:143], v[160:161], v[134:135]
	v_pk_mul_f32 v[144:145], v[160:161], s[48:49] op_sel_hi:[1,0]
	v_pk_mul_f32 v[140:141], v[162:163], s[48:49] op_sel_hi:[1,0]
	v_pk_mul_f32 v[134:135], v[164:165], v[138:139]
	v_pk_mul_f32 v[138:139], v[162:163], v[136:137]
	s_waitcnt lgkmcnt(0)
	v_pk_mul_f32 v[160:161], v[150:151], v[156:157] op_sel_hi:[1,0]
	v_mul_f32_e32 v162, v156, v156
	v_pk_mul_f32 v[160:161], v[160:161], v[158:159]
	v_pk_mul_f32 v[124:125], v[158:159], v[124:125]
	v_pk_mul_f32 v[158:159], v[146:147], v[162:163] op_sel_hi:[1,0]
	v_pk_mul_f32 v[126:127], v[130:131], v[126:127]
	v_pk_mul_f32 v[124:125], v[124:125], v[158:159]
	v_pk_mul_f32 v[158:159], v[144:145], v[156:157] op_sel_hi:[1,0]
	v_cvt_f32_i32_e32 v117, v117
	v_pk_mul_f32 v[158:159], v[158:159], v[130:131]
	v_cvt_f32_i32_e32 v131, v121
	v_cvt_f32_i32_e32 v130, v120
	v_pk_mul_f32 v[120:121], v[142:143], v[162:163] op_sel_hi:[1,0]
	v_cvt_f32_i32_e32 v116, v116
	v_pk_mul_f32 v[120:121], v[126:127], v[120:121]
	v_pk_mul_f32 v[126:127], v[140:141], v[156:157] op_sel_hi:[1,0]
	v_cvt_f32_i32_e32 v123, v123
	v_pk_mul_f32 v[126:127], v[126:127], v[130:131]
	v_cvt_f32_i32_e32 v122, v122
	v_exp_f32_e32 v126, v126
	v_exp_f32_e32 v127, v127
	v_pk_mul_f32 v[136:137], v[164:165], s[48:49] op_sel_hi:[1,0]
	v_pk_mul_f32 v[116:117], v[130:131], v[116:117]
	v_pk_mul_f32 v[130:131], v[138:139], v[162:163] op_sel_hi:[1,0]
	v_pk_add_f32 v[126:127], v[126:127], 1.0 op_sel_hi:[1,0]
	v_pk_mul_f32 v[116:117], v[116:117], v[130:131]
	v_pk_mul_f32 v[130:131], v[136:137], v[156:157] op_sel_hi:[1,0]
	v_exp_f32_e32 v160, v160
	v_pk_mul_f32 v[130:131], v[130:131], v[122:123]
	v_exp_f32_e32 v161, v161
	v_exp_f32_e32 v158, v158
	v_exp_f32_e32 v159, v159
	v_rcp_f32_e32 v126, v126
	v_rcp_f32_e32 v127, v127
	v_exp_f32_e32 v130, v130
	v_exp_f32_e32 v131, v131
	v_cvt_f32_i32_e32 v119, v119
	v_cvt_f32_i32_e32 v118, v118
	v_pk_add_f32 v[160:161], v[160:161], 1.0 op_sel_hi:[1,0]
	v_pk_add_f32 v[158:159], v[158:159], 1.0 op_sel_hi:[1,0]
	v_pk_mul_f32 v[116:117], v[116:117], v[126:127]
	v_pk_add_f32 v[126:127], v[130:131], 1.0 op_sel_hi:[1,0]
	v_rcp_f32_e32 v160, v160
	v_rcp_f32_e32 v161, v161
	v_rcp_f32_e32 v158, v158
	v_rcp_f32_e32 v159, v159
	v_rcp_f32_e32 v126, v126
	v_rcp_f32_e32 v127, v127
	v_or_b32_e32 v132, s30, v167
	v_pk_mul_f32 v[118:119], v[122:123], v[118:119]
	v_pk_mul_f32 v[122:123], v[134:135], v[162:163] op_sel_hi:[1,0]
	v_or_b32_e32 v132, s17, v132
	v_or_b32_e32 v133, s21, v166
	v_pk_mul_f32 v[118:119], v[118:119], v[122:123]
	v_cndmask_b32_e64 v122, 0, 1, s[4:5]
	v_lshl_add_u32 v128, s26, 8, v133
	v_ashrrev_i32_e32 v133, 31, v132
	v_pk_mul_f32 v[124:125], v[124:125], v[160:161]
	v_pk_mul_f32 v[120:121], v[120:121], v[158:159]
	v_pk_mul_f32 v[118:119], v[118:119], v[126:127]
	v_cmp_ne_u32_e64 s[42:43], 1, v122
	s_andn2_b64 vcc, exec, s[4:5]
	s_mov_b64 s[26:27], -1
	s_cbranch_vccnz .LBB0_299
	v_cvt_pk_fp8_f32 v122, v124, v125
	v_cvt_pk_fp8_f32 v123, v116, v117
	v_mad_u32_u24 v126, v128, s92, v132
	v_cvt_pk_fp8_f32 v122, v120, v121 op_sel:[0,0,1]
	v_cvt_pk_fp8_f32 v123, v118, v119 op_sel:[0,0,1]
	s_mov_b64 s[26:27], 0
	global_store_dwordx2 v126, v[122:123], s[8:9]

.LBB0_301:
	v_cvt_f32_i32_e32 v113, v113
	v_cvt_f32_i32_e32 v112, v112
	v_cvt_f32_i32_e32 v109, v109
	v_cvt_f32_i32_e32 v108, v108
	v_mov_b32_e32 v116, v157
	v_pk_mul_f32 v[118:119], v[150:151], v[116:117] op_sel_hi:[1,0]
	v_cvt_f32_i32_e32 v111, v111
	v_pk_mul_f32 v[118:119], v[118:119], v[112:113]
	v_pk_mul_f32 v[108:109], v[112:113], v[108:109]
	v_cvt_f32_i32_e32 v113, v115
	v_cvt_f32_i32_e32 v112, v114
	v_cvt_f32_i32_e32 v110, v110
	v_mul_f32_e32 v120, v157, v157
	v_pk_mul_f32 v[114:115], v[146:147], v[120:121] op_sel_hi:[1,0]
	v_cvt_f32_i32_e32 v101, v101
	v_pk_mul_f32 v[108:109], v[108:109], v[114:115]
	v_pk_mul_f32 v[114:115], v[144:145], v[116:117] op_sel_hi:[1,0]
	v_pk_mul_f32 v[110:111], v[112:113], v[110:111]
	v_pk_mul_f32 v[114:115], v[114:115], v[112:113]
	v_cvt_f32_i32_e32 v113, v105
	v_cvt_f32_i32_e32 v112, v104
	v_pk_mul_f32 v[104:105], v[142:143], v[120:121] op_sel_hi:[1,0]
	v_cvt_f32_i32_e32 v100, v100
	v_pk_mul_f32 v[104:105], v[110:111], v[104:105]
	v_pk_mul_f32 v[110:111], v[140:141], v[116:117] op_sel_hi:[1,0]
	v_cvt_f32_i32_e32 v107, v107
	v_pk_mul_f32 v[110:111], v[110:111], v[112:113]
	v_cvt_f32_i32_e32 v106, v106
	v_exp_f32_e32 v110, v110
	v_exp_f32_e32 v111, v111
	v_pk_mul_f32 v[100:101], v[112:113], v[100:101]
	v_pk_mul_f32 v[112:113], v[138:139], v[120:121] op_sel_hi:[1,0]
	v_exp_f32_e32 v118, v118
	v_pk_mul_f32 v[100:101], v[100:101], v[112:113]
	v_pk_mul_f32 v[112:113], v[136:137], v[116:117] op_sel_hi:[1,0]
	v_pk_add_f32 v[110:111], v[110:111], 1.0 op_sel_hi:[1,0]
	v_pk_mul_f32 v[112:113], v[112:113], v[106:107]
	v_exp_f32_e32 v119, v119
	v_exp_f32_e32 v114, v114
	v_exp_f32_e32 v115, v115
	v_rcp_f32_e32 v110, v110
	v_rcp_f32_e32 v111, v111
	v_exp_f32_e32 v112, v112
	v_exp_f32_e32 v113, v113
	v_cvt_f32_i32_e32 v103, v103
	v_cvt_f32_i32_e32 v102, v102
	v_pk_add_f32 v[118:119], v[118:119], 1.0 op_sel_hi:[1,0]
	v_pk_add_f32 v[114:115], v[114:115], 1.0 op_sel_hi:[1,0]
	v_pk_mul_f32 v[100:101], v[100:101], v[110:111]
	v_pk_add_f32 v[110:111], v[112:113], 1.0 op_sel_hi:[1,0]
	v_rcp_f32_e32 v118, v118
	v_rcp_f32_e32 v119, v119
	v_rcp_f32_e32 v114, v114
	v_rcp_f32_e32 v115, v115
	v_rcp_f32_e32 v110, v110
	v_rcp_f32_e32 v111, v111
	v_pk_mul_f32 v[102:103], v[106:107], v[102:103]
	v_pk_mul_f32 v[106:107], v[134:135], v[120:121] op_sel_hi:[1,0]
	v_pk_mul_f32 v[108:109], v[108:109], v[118:119]
	v_pk_mul_f32 v[102:103], v[102:103], v[106:107]
	v_pk_mul_f32 v[104:105], v[104:105], v[114:115]
	v_pk_mul_f32 v[102:103], v[102:103], v[110:111]
	v_or_b32_e32 v106, 16, v128
	s_and_b64 vcc, exec, s[42:43]
	s_mov_b64 s[26:27], -1
	s_cbranch_vccnz .LBB0_303
	v_cvt_pk_fp8_f32 v110, v108, v109
	v_cvt_pk_fp8_f32 v111, v100, v101
	v_mad_u32_u24 v112, v106, s92, v132
	v_cvt_pk_fp8_f32 v110, v104, v105 op_sel:[0,0,1]
	v_cvt_pk_fp8_f32 v111, v102, v103 op_sel:[0,0,1]
	s_mov_b64 s[26:27], 0
	global_store_dwordx2 v112, v[110:111], s[8:9]

.LBB0_305:
	v_cvt_f32_i32_e32 v97, v97
	v_cvt_f32_i32_e32 v96, v96
	v_cvt_f32_i32_e32 v93, v93
	v_cvt_f32_i32_e32 v92, v92
	v_pk_mul_f32 v[100:101], v[150:151], v[154:155] op_sel_hi:[1,0]
	v_cvt_f32_i32_e32 v95, v95
	v_pk_mul_f32 v[100:101], v[100:101], v[96:97]
	v_pk_mul_f32 v[92:93], v[96:97], v[92:93]
	v_cvt_f32_i32_e32 v97, v99
	v_cvt_f32_i32_e32 v96, v98
	v_cvt_f32_i32_e32 v94, v94
	v_mul_f32_e32 v102, v154, v154
	v_pk_mul_f32 v[98:99], v[146:147], v[102:103] op_sel_hi:[1,0]
	v_cvt_f32_i32_e32 v85, v85
	v_pk_mul_f32 v[92:93], v[92:93], v[98:99]
	v_pk_mul_f32 v[98:99], v[144:145], v[154:155] op_sel_hi:[1,0]
	v_pk_mul_f32 v[94:95], v[96:97], v[94:95]
	v_pk_mul_f32 v[98:99], v[98:99], v[96:97]
	v_cvt_f32_i32_e32 v97, v89
	v_cvt_f32_i32_e32 v96, v88
	v_pk_mul_f32 v[88:89], v[142:143], v[102:103] op_sel_hi:[1,0]
	v_cvt_f32_i32_e32 v84, v84
	v_pk_mul_f32 v[88:89], v[94:95], v[88:89]
	v_pk_mul_f32 v[94:95], v[140:141], v[154:155] op_sel_hi:[1,0]
	v_cvt_f32_i32_e32 v91, v91
	v_pk_mul_f32 v[94:95], v[94:95], v[96:97]
	v_cvt_f32_i32_e32 v90, v90
	v_exp_f32_e32 v94, v94
	v_exp_f32_e32 v95, v95
	v_pk_mul_f32 v[84:85], v[96:97], v[84:85]
	v_pk_mul_f32 v[96:97], v[138:139], v[102:103] op_sel_hi:[1,0]
	v_exp_f32_e32 v100, v100
	v_pk_mul_f32 v[84:85], v[84:85], v[96:97]
	v_pk_mul_f32 v[96:97], v[136:137], v[154:155] op_sel_hi:[1,0]
	v_pk_add_f32 v[94:95], v[94:95], 1.0 op_sel_hi:[1,0]
	v_pk_mul_f32 v[96:97], v[96:97], v[90:91]
	v_exp_f32_e32 v101, v101
	v_exp_f32_e32 v98, v98
	v_exp_f32_e32 v99, v99
	v_rcp_f32_e32 v94, v94
	v_rcp_f32_e32 v95, v95
	v_exp_f32_e32 v96, v96
	v_exp_f32_e32 v97, v97
	v_cvt_f32_i32_e32 v87, v87
	v_cvt_f32_i32_e32 v86, v86
	v_pk_add_f32 v[100:101], v[100:101], 1.0 op_sel_hi:[1,0]
	v_pk_add_f32 v[98:99], v[98:99], 1.0 op_sel_hi:[1,0]
	v_pk_mul_f32 v[84:85], v[84:85], v[94:95]
	v_pk_add_f32 v[94:95], v[96:97], 1.0 op_sel_hi:[1,0]
	v_rcp_f32_e32 v100, v100
	v_rcp_f32_e32 v101, v101
	v_rcp_f32_e32 v98, v98
	v_rcp_f32_e32 v99, v99
	v_rcp_f32_e32 v94, v94
	v_rcp_f32_e32 v95, v95
	v_pk_mul_f32 v[86:87], v[90:91], v[86:87]
	v_pk_mul_f32 v[90:91], v[134:135], v[102:103] op_sel_hi:[1,0]
	v_pk_mul_f32 v[92:93], v[92:93], v[100:101]
	v_pk_mul_f32 v[86:87], v[86:87], v[90:91]
	v_pk_mul_f32 v[88:89], v[88:89], v[98:99]
	v_pk_mul_f32 v[86:87], v[86:87], v[94:95]
	v_or_b32_e32 v90, 32, v128
	s_and_b64 vcc, exec, s[42:43]
	s_mov_b64 s[26:27], -1
	s_cbranch_vccnz .LBB0_307
	v_cvt_pk_fp8_f32 v94, v92, v93
	v_cvt_pk_fp8_f32 v95, v84, v85
	v_mad_u32_u24 v96, v90, s92, v132
	v_cvt_pk_fp8_f32 v94, v88, v89 op_sel:[0,0,1]
	v_cvt_pk_fp8_f32 v95, v86, v87 op_sel:[0,0,1]
	s_mov_b64 s[26:27], 0
	global_store_dwordx2 v96, v[94:95], s[8:9]

.LBB0_309:
	v_cvt_f32_i32_e32 v81, v81
	v_cvt_f32_i32_e32 v80, v80
	v_cvt_f32_i32_e32 v77, v77
	v_cvt_f32_i32_e32 v76, v76
	v_mov_b32_e32 v84, v155
	v_pk_mul_f32 v[86:87], v[150:151], v[84:85] op_sel_hi:[1,0]
	v_cvt_f32_i32_e32 v79, v79
	v_pk_mul_f32 v[86:87], v[86:87], v[80:81]
	v_pk_mul_f32 v[76:77], v[80:81], v[76:77]
	v_cvt_f32_i32_e32 v81, v83
	v_cvt_f32_i32_e32 v80, v82
	v_cvt_f32_i32_e32 v78, v78
	v_mul_f32_e32 v88, v155, v155
	v_pk_mul_f32 v[82:83], v[146:147], v[88:89] op_sel_hi:[1,0]
	v_cvt_f32_i32_e32 v69, v69
	v_pk_mul_f32 v[76:77], v[76:77], v[82:83]
	v_pk_mul_f32 v[82:83], v[144:145], v[84:85] op_sel_hi:[1,0]
	v_pk_mul_f32 v[78:79], v[80:81], v[78:79]
	v_pk_mul_f32 v[82:83], v[82:83], v[80:81]
	v_cvt_f32_i32_e32 v81, v73
	v_cvt_f32_i32_e32 v80, v72
	v_pk_mul_f32 v[72:73], v[142:143], v[88:89] op_sel_hi:[1,0]
	v_cvt_f32_i32_e32 v68, v68
	v_pk_mul_f32 v[72:73], v[78:79], v[72:73]
	v_pk_mul_f32 v[78:79], v[140:141], v[84:85] op_sel_hi:[1,0]
	v_cvt_f32_i32_e32 v75, v75
	v_pk_mul_f32 v[78:79], v[78:79], v[80:81]
	v_cvt_f32_i32_e32 v74, v74
	v_exp_f32_e32 v78, v78
	v_exp_f32_e32 v79, v79
	v_pk_mul_f32 v[68:69], v[80:81], v[68:69]
	v_pk_mul_f32 v[80:81], v[138:139], v[88:89] op_sel_hi:[1,0]
	v_exp_f32_e32 v86, v86
	v_pk_mul_f32 v[68:69], v[68:69], v[80:81]
	v_pk_mul_f32 v[80:81], v[136:137], v[84:85] op_sel_hi:[1,0]
	v_pk_add_f32 v[78:79], v[78:79], 1.0 op_sel_hi:[1,0]
	v_pk_mul_f32 v[80:81], v[80:81], v[74:75]
	v_exp_f32_e32 v87, v87
	v_exp_f32_e32 v82, v82
	v_exp_f32_e32 v83, v83
	v_rcp_f32_e32 v78, v78
	v_rcp_f32_e32 v79, v79
	v_exp_f32_e32 v80, v80
	v_exp_f32_e32 v81, v81
	v_cvt_f32_i32_e32 v71, v71
	v_cvt_f32_i32_e32 v70, v70
	v_pk_add_f32 v[86:87], v[86:87], 1.0 op_sel_hi:[1,0]
	v_pk_add_f32 v[82:83], v[82:83], 1.0 op_sel_hi:[1,0]
	v_pk_mul_f32 v[68:69], v[68:69], v[78:79]
	v_pk_add_f32 v[78:79], v[80:81], 1.0 op_sel_hi:[1,0]
	v_rcp_f32_e32 v86, v86
	v_rcp_f32_e32 v87, v87
	v_rcp_f32_e32 v82, v82
	v_rcp_f32_e32 v83, v83
	v_rcp_f32_e32 v78, v78
	v_rcp_f32_e32 v79, v79
	v_pk_mul_f32 v[70:71], v[74:75], v[70:71]
	v_pk_mul_f32 v[74:75], v[134:135], v[88:89] op_sel_hi:[1,0]
	v_pk_mul_f32 v[76:77], v[76:77], v[86:87]
	v_pk_mul_f32 v[70:71], v[70:71], v[74:75]
	v_pk_mul_f32 v[72:73], v[72:73], v[82:83]
	v_pk_mul_f32 v[70:71], v[70:71], v[78:79]
	v_or_b32_e32 v74, 48, v128
	s_and_b64 vcc, exec, s[42:43]
	s_mov_b64 s[26:27], -1
	s_cbranch_vccnz .LBB0_311
	v_cvt_pk_fp8_f32 v78, v76, v77
	v_cvt_pk_fp8_f32 v79, v68, v69
	v_mad_u32_u24 v80, v74, s92, v132
	v_cvt_pk_fp8_f32 v78, v72, v73 op_sel:[0,0,1]
	v_cvt_pk_fp8_f32 v79, v70, v71 op_sel:[0,0,1]
	s_mov_b64 s[26:27], 0
	global_store_dwordx2 v80, v[78:79], s[8:9]

.LBB0_313:
	v_cvt_f32_i32_e32 v69, v65
	v_cvt_f32_i32_e32 v68, v64
	v_cvt_f32_i32_e32 v61, v61
	v_cvt_f32_i32_e32 v60, v60
	v_cvt_f32_i32_e32 v67, v67
	v_cvt_f32_i32_e32 v66, v66
	v_cvt_f32_i32_e32 v63, v63
	v_cvt_f32_i32_e32 v62, v62
	v_pk_mul_f32 v[70:71], v[150:151], v[152:153] op_sel_hi:[1,0]
	v_mul_f32_e32 v72, v152, v152
	v_pk_mul_f32 v[70:71], v[70:71], v[68:69]
	v_pk_mul_f32 v[60:61], v[68:69], v[60:61]
	v_pk_mul_f32 v[68:69], v[146:147], v[72:73] op_sel_hi:[1,0]
	v_pk_mul_f32 v[62:63], v[66:67], v[62:63]
	v_pk_mul_f32 v[60:61], v[60:61], v[68:69]
	v_pk_mul_f32 v[68:69], v[144:145], v[152:153] op_sel_hi:[1,0]
	v_cvt_f32_i32_e32 v53, v53
	v_pk_mul_f32 v[68:69], v[68:69], v[66:67]
	v_cvt_f32_i32_e32 v67, v57
	v_cvt_f32_i32_e32 v66, v56
	v_pk_mul_f32 v[56:57], v[142:143], v[72:73] op_sel_hi:[1,0]
	v_cvt_f32_i32_e32 v52, v52
	v_pk_mul_f32 v[56:57], v[62:63], v[56:57]
	v_pk_mul_f32 v[62:63], v[140:141], v[152:153] op_sel_hi:[1,0]
	v_cvt_f32_i32_e32 v59, v59
	v_pk_mul_f32 v[62:63], v[62:63], v[66:67]
	v_cvt_f32_i32_e32 v58, v58
	v_exp_f32_e32 v62, v62
	v_exp_f32_e32 v63, v63
	v_pk_mul_f32 v[52:53], v[66:67], v[52:53]
	v_pk_mul_f32 v[66:67], v[138:139], v[72:73] op_sel_hi:[1,0]
	v_exp_f32_e32 v70, v70
	v_pk_mul_f32 v[52:53], v[52:53], v[66:67]
	v_pk_mul_f32 v[66:67], v[136:137], v[152:153] op_sel_hi:[1,0]
	v_pk_add_f32 v[62:63], v[62:63], 1.0 op_sel_hi:[1,0]
	v_pk_mul_f32 v[66:67], v[66:67], v[58:59]
	v_exp_f32_e32 v71, v71
	v_exp_f32_e32 v68, v68
	v_exp_f32_e32 v69, v69
	v_rcp_f32_e32 v62, v62
	v_rcp_f32_e32 v63, v63
	v_exp_f32_e32 v66, v66
	v_exp_f32_e32 v67, v67
	v_cvt_f32_i32_e32 v55, v55
	v_cvt_f32_i32_e32 v54, v54
	v_pk_add_f32 v[70:71], v[70:71], 1.0 op_sel_hi:[1,0]
	v_pk_add_f32 v[68:69], v[68:69], 1.0 op_sel_hi:[1,0]
	v_pk_mul_f32 v[52:53], v[52:53], v[62:63]
	v_pk_add_f32 v[62:63], v[66:67], 1.0 op_sel_hi:[1,0]
	v_rcp_f32_e32 v70, v70
	v_rcp_f32_e32 v71, v71
	v_rcp_f32_e32 v68, v68
	v_rcp_f32_e32 v69, v69
	v_rcp_f32_e32 v62, v62
	v_rcp_f32_e32 v63, v63
	v_pk_mul_f32 v[54:55], v[58:59], v[54:55]
	v_pk_mul_f32 v[58:59], v[134:135], v[72:73] op_sel_hi:[1,0]
	v_add_u32_e32 v64, 0x80, v128
	v_pk_mul_f32 v[54:55], v[54:55], v[58:59]
	v_pk_mul_f32 v[60:61], v[60:61], v[70:71]
	v_pk_mul_f32 v[56:57], v[56:57], v[68:69]
	v_pk_mul_f32 v[54:55], v[54:55], v[62:63]
	s_and_b64 vcc, exec, s[42:43]
	s_mov_b64 s[26:27], -1
	s_cbranch_vccnz .LBB0_315
	v_cvt_pk_fp8_f32 v58, v60, v61
	v_cvt_pk_fp8_f32 v59, v52, v53
	v_mad_u32_u24 v62, v64, s92, v132
	v_cvt_pk_fp8_f32 v58, v56, v57 op_sel:[0,0,1]
	v_cvt_pk_fp8_f32 v59, v54, v55 op_sel:[0,0,1]
	s_mov_b64 s[26:27], 0
	global_store_dwordx2 v62, v[58:59], s[8:9]

.LBB0_317:
	v_cvt_f32_i32_e32 v49, v49
	v_cvt_f32_i32_e32 v48, v48
	v_cvt_f32_i32_e32 v45, v45
	v_cvt_f32_i32_e32 v44, v44
	v_mov_b32_e32 v52, v153
	v_pk_mul_f32 v[54:55], v[150:151], v[52:53] op_sel_hi:[1,0]
	v_cvt_f32_i32_e32 v47, v47
	v_pk_mul_f32 v[54:55], v[54:55], v[48:49]
	v_pk_mul_f32 v[44:45], v[48:49], v[44:45]
	v_cvt_f32_i32_e32 v49, v51
	v_cvt_f32_i32_e32 v48, v50
	v_cvt_f32_i32_e32 v46, v46
	v_mul_f32_e32 v56, v153, v153
	v_pk_mul_f32 v[50:51], v[146:147], v[56:57] op_sel_hi:[1,0]
	v_cvt_f32_i32_e32 v37, v37
	v_pk_mul_f32 v[44:45], v[44:45], v[50:51]
	v_pk_mul_f32 v[50:51], v[144:145], v[52:53] op_sel_hi:[1,0]
	v_pk_mul_f32 v[46:47], v[48:49], v[46:47]
	v_pk_mul_f32 v[50:51], v[50:51], v[48:49]
	v_cvt_f32_i32_e32 v49, v41
	v_cvt_f32_i32_e32 v48, v40
	v_pk_mul_f32 v[40:41], v[142:143], v[56:57] op_sel_hi:[1,0]
	v_cvt_f32_i32_e32 v36, v36
	v_pk_mul_f32 v[40:41], v[46:47], v[40:41]
	v_pk_mul_f32 v[46:47], v[140:141], v[52:53] op_sel_hi:[1,0]
	v_cvt_f32_i32_e32 v43, v43
	v_pk_mul_f32 v[46:47], v[46:47], v[48:49]
	v_cvt_f32_i32_e32 v42, v42
	v_exp_f32_e32 v46, v46
	v_exp_f32_e32 v47, v47
	v_pk_mul_f32 v[36:37], v[48:49], v[36:37]
	v_pk_mul_f32 v[48:49], v[138:139], v[56:57] op_sel_hi:[1,0]
	v_exp_f32_e32 v54, v54
	v_pk_mul_f32 v[36:37], v[36:37], v[48:49]
	v_pk_mul_f32 v[48:49], v[136:137], v[52:53] op_sel_hi:[1,0]
	v_pk_add_f32 v[46:47], v[46:47], 1.0 op_sel_hi:[1,0]
	v_pk_mul_f32 v[48:49], v[48:49], v[42:43]
	v_exp_f32_e32 v55, v55
	v_exp_f32_e32 v50, v50
	v_exp_f32_e32 v51, v51
	v_rcp_f32_e32 v46, v46
	v_rcp_f32_e32 v47, v47
	v_exp_f32_e32 v48, v48
	v_exp_f32_e32 v49, v49
	v_cvt_f32_i32_e32 v39, v39
	v_cvt_f32_i32_e32 v38, v38
	v_pk_add_f32 v[54:55], v[54:55], 1.0 op_sel_hi:[1,0]
	v_pk_add_f32 v[50:51], v[50:51], 1.0 op_sel_hi:[1,0]
	v_pk_mul_f32 v[36:37], v[36:37], v[46:47]
	v_pk_add_f32 v[46:47], v[48:49], 1.0 op_sel_hi:[1,0]
	v_rcp_f32_e32 v54, v54
	v_rcp_f32_e32 v55, v55
	v_rcp_f32_e32 v50, v50
	v_rcp_f32_e32 v51, v51
	v_rcp_f32_e32 v46, v46
	v_rcp_f32_e32 v47, v47
	v_pk_mul_f32 v[38:39], v[42:43], v[38:39]
	v_pk_mul_f32 v[42:43], v[134:135], v[56:57] op_sel_hi:[1,0]
	v_pk_mul_f32 v[44:45], v[44:45], v[54:55]
	v_pk_mul_f32 v[38:39], v[38:39], v[42:43]
	v_pk_mul_f32 v[40:41], v[40:41], v[50:51]
	v_pk_mul_f32 v[38:39], v[38:39], v[46:47]
	v_add_u32_e32 v42, 0x90, v128
	s_and_b64 vcc, exec, s[42:43]
	s_mov_b64 s[26:27], -1
	s_cbranch_vccnz .LBB0_319
	v_cvt_pk_fp8_f32 v46, v44, v45
	v_cvt_pk_fp8_f32 v47, v36, v37
	v_mad_u32_u24 v48, v42, s92, v132
	v_cvt_pk_fp8_f32 v46, v40, v41 op_sel:[0,0,1]
	v_cvt_pk_fp8_f32 v47, v38, v39 op_sel:[0,0,1]
	s_mov_b64 s[26:27], 0
	global_store_dwordx2 v48, v[46:47], s[8:9]

.LBB0_321:
	v_cvt_f32_i32_e32 v31, v31
	v_cvt_f32_i32_e32 v30, v30
	v_cvt_f32_i32_e32 v27, v27
	v_cvt_f32_i32_e32 v26, v26
	v_pk_mul_f32 v[36:37], v[150:151], v[148:149] op_sel_hi:[1,0]
	v_cvt_f32_i32_e32 v29, v29
	v_pk_mul_f32 v[36:37], v[36:37], v[30:31]
	v_pk_mul_f32 v[26:27], v[30:31], v[26:27]
	v_cvt_f32_i32_e32 v31, v33
	v_cvt_f32_i32_e32 v30, v32
	v_cvt_f32_i32_e32 v28, v28
	v_mul_f32_e32 v38, v148, v148
	v_pk_mul_f32 v[32:33], v[146:147], v[38:39] op_sel_hi:[1,0]
	v_cvt_f32_i32_e32 v19, v19
	v_pk_mul_f32 v[26:27], v[26:27], v[32:33]
	v_pk_mul_f32 v[32:33], v[144:145], v[148:149] op_sel_hi:[1,0]
	v_pk_mul_f32 v[28:29], v[30:31], v[28:29]
	v_pk_mul_f32 v[32:33], v[32:33], v[30:31]
	v_cvt_f32_i32_e32 v31, v23
	v_cvt_f32_i32_e32 v30, v22
	v_pk_mul_f32 v[22:23], v[142:143], v[38:39] op_sel_hi:[1,0]
	v_cvt_f32_i32_e32 v18, v18
	v_pk_mul_f32 v[22:23], v[28:29], v[22:23]
	v_pk_mul_f32 v[28:29], v[140:141], v[148:149] op_sel_hi:[1,0]
	v_cvt_f32_i32_e32 v25, v25
	v_pk_mul_f32 v[28:29], v[28:29], v[30:31]
	v_cvt_f32_i32_e32 v24, v24
	v_exp_f32_e32 v28, v28
	v_exp_f32_e32 v29, v29
	v_pk_mul_f32 v[18:19], v[30:31], v[18:19]
	v_pk_mul_f32 v[30:31], v[138:139], v[38:39] op_sel_hi:[1,0]
	v_exp_f32_e32 v36, v36
	v_pk_mul_f32 v[18:19], v[18:19], v[30:31]
	v_pk_mul_f32 v[30:31], v[136:137], v[148:149] op_sel_hi:[1,0]
	v_pk_add_f32 v[28:29], v[28:29], 1.0 op_sel_hi:[1,0]
	v_pk_mul_f32 v[30:31], v[30:31], v[24:25]
	v_exp_f32_e32 v37, v37
	v_exp_f32_e32 v32, v32
	v_exp_f32_e32 v33, v33
	v_rcp_f32_e32 v28, v28
	v_rcp_f32_e32 v29, v29
	v_exp_f32_e32 v30, v30
	v_exp_f32_e32 v31, v31
	v_cvt_f32_i32_e32 v21, v21
	v_cvt_f32_i32_e32 v20, v20
	v_pk_add_f32 v[36:37], v[36:37], 1.0 op_sel_hi:[1,0]
	v_pk_add_f32 v[32:33], v[32:33], 1.0 op_sel_hi:[1,0]
	v_pk_mul_f32 v[18:19], v[18:19], v[28:29]
	v_pk_add_f32 v[28:29], v[30:31], 1.0 op_sel_hi:[1,0]
	v_rcp_f32_e32 v36, v36
	v_rcp_f32_e32 v37, v37
	v_rcp_f32_e32 v32, v32
	v_rcp_f32_e32 v33, v33
	v_rcp_f32_e32 v28, v28
	v_rcp_f32_e32 v29, v29
	v_pk_mul_f32 v[20:21], v[24:25], v[20:21]
	v_pk_mul_f32 v[24:25], v[134:135], v[38:39] op_sel_hi:[1,0]
	v_pk_mul_f32 v[26:27], v[26:27], v[36:37]
	v_pk_mul_f32 v[20:21], v[20:21], v[24:25]
	v_pk_mul_f32 v[22:23], v[22:23], v[32:33]
	v_pk_mul_f32 v[20:21], v[20:21], v[28:29]
	v_add_u32_e32 v24, 0xa0, v128
	s_and_b64 vcc, exec, s[42:43]
	s_mov_b64 s[26:27], -1
	s_cbranch_vccnz .LBB0_323
	v_cvt_pk_fp8_f32 v28, v26, v27
	v_cvt_pk_fp8_f32 v29, v18, v19
	v_mad_u32_u24 v30, v24, s92, v132
	v_cvt_pk_fp8_f32 v28, v22, v23 op_sel:[0,0,1]
	v_cvt_pk_fp8_f32 v29, v20, v21 op_sel:[0,0,1]
	s_mov_b64 s[26:27], 0
	global_store_dwordx2 v30, v[28:29], s[8:9]

.LBB0_325:
	v_cvt_f32_i32_e32 v15, v15
	v_cvt_f32_i32_e32 v14, v14
	v_cvt_f32_i32_e32 v11, v11
	v_cvt_f32_i32_e32 v10, v10
	v_mov_b32_e32 v18, v149
	v_pk_mul_f32 v[20:21], v[150:151], v[18:19] op_sel_hi:[1,0]
	v_cvt_f32_i32_e32 v13, v13
	v_pk_mul_f32 v[20:21], v[20:21], v[14:15]
	v_pk_mul_f32 v[10:11], v[14:15], v[10:11]
	v_cvt_f32_i32_e32 v15, v17
	v_cvt_f32_i32_e32 v14, v16
	v_cvt_f32_i32_e32 v12, v12
	v_mul_f32_e32 v22, v149, v149
	v_pk_mul_f32 v[16:17], v[146:147], v[22:23] op_sel_hi:[1,0]
	v_cvt_f32_i32_e32 v3, v3
	v_pk_mul_f32 v[10:11], v[10:11], v[16:17]
	v_pk_mul_f32 v[16:17], v[144:145], v[18:19] op_sel_hi:[1,0]
	v_pk_mul_f32 v[12:13], v[14:15], v[12:13]
	v_pk_mul_f32 v[16:17], v[16:17], v[14:15]
	v_cvt_f32_i32_e32 v15, v7
	v_cvt_f32_i32_e32 v14, v6
	v_pk_mul_f32 v[6:7], v[142:143], v[22:23] op_sel_hi:[1,0]
	v_cvt_f32_i32_e32 v2, v2
	v_pk_mul_f32 v[6:7], v[12:13], v[6:7]
	v_pk_mul_f32 v[12:13], v[140:141], v[18:19] op_sel_hi:[1,0]
	v_cvt_f32_i32_e32 v9, v9
	v_pk_mul_f32 v[12:13], v[12:13], v[14:15]
	v_cvt_f32_i32_e32 v8, v8
	v_exp_f32_e32 v12, v12
	v_exp_f32_e32 v13, v13
	v_pk_mul_f32 v[2:3], v[14:15], v[2:3]
	v_pk_mul_f32 v[14:15], v[138:139], v[22:23] op_sel_hi:[1,0]
	v_exp_f32_e32 v20, v20
	v_pk_mul_f32 v[2:3], v[2:3], v[14:15]
	v_pk_mul_f32 v[14:15], v[136:137], v[18:19] op_sel_hi:[1,0]
	v_pk_add_f32 v[12:13], v[12:13], 1.0 op_sel_hi:[1,0]
	v_pk_mul_f32 v[14:15], v[14:15], v[8:9]
	v_exp_f32_e32 v21, v21
	v_exp_f32_e32 v16, v16
	v_exp_f32_e32 v17, v17
	v_rcp_f32_e32 v12, v12
	v_rcp_f32_e32 v13, v13
	v_exp_f32_e32 v14, v14
	v_exp_f32_e32 v15, v15
	v_cvt_f32_i32_e32 v5, v5
	v_cvt_f32_i32_e32 v4, v4
	v_pk_add_f32 v[20:21], v[20:21], 1.0 op_sel_hi:[1,0]
	v_pk_add_f32 v[16:17], v[16:17], 1.0 op_sel_hi:[1,0]
	v_pk_mul_f32 v[2:3], v[2:3], v[12:13]
	v_pk_add_f32 v[12:13], v[14:15], 1.0 op_sel_hi:[1,0]
	v_rcp_f32_e32 v20, v20
	v_rcp_f32_e32 v21, v21
	v_rcp_f32_e32 v16, v16
	v_rcp_f32_e32 v17, v17
	v_rcp_f32_e32 v12, v12
	v_rcp_f32_e32 v13, v13
	v_pk_mul_f32 v[4:5], v[8:9], v[4:5]
	v_pk_mul_f32 v[8:9], v[134:135], v[22:23] op_sel_hi:[1,0]
	v_pk_mul_f32 v[10:11], v[10:11], v[20:21]
	v_pk_mul_f32 v[4:5], v[4:5], v[8:9]
	v_pk_mul_f32 v[6:7], v[6:7], v[16:17]
	v_pk_mul_f32 v[4:5], v[4:5], v[12:13]
	v_add_u32_e32 v8, 0xb0, v128
	s_and_b64 vcc, exec, s[42:43]
	s_mov_b64 s[26:27], -1
	s_cbranch_vccnz .LBB0_328
	v_cvt_pk_fp8_f32 v12, v10, v11
	v_cvt_pk_fp8_f32 v13, v2, v3
	v_mad_u32_u24 v14, v8, s92, v132
	v_cvt_pk_fp8_f32 v12, v6, v7 op_sel:[0,0,1]
	v_cvt_pk_fp8_f32 v13, v4, v5 op_sel:[0,0,1]
	global_store_dwordx2 v14, v[12:13], s[8:9]
	s_cbranch_execz .LBB0_329
